# kv up-proj epilogue: V^T written through a per-wave LDS transpose with 16-byte stores (was 2-byte scattered stores)
# speedup vs baseline: 1.0010x; 1.0010x over previous
; __device__ __forceinline__ unsigned cvt_pk_bf16(float lo, float hi) { f32x2_t v = {lo, hi}; bf16x2_t b = __builtin_convertvector(v, bf16x2_t); return __builtin_bit_cast(unsigned, b); }
; __device__ __forceinline__ int p16(int k) { return ((k >> 2) & 1) * 8 + (k >> 3) * 4 + (k & 3); }
; __device__ __forceinline__ v4u pack8(f32x4 a, f32x4 b) { v4u r; r.x = cvt_pk_bf16(a[0], a[1]); r.y = cvt_pk_bf16(a[2], a[3]); r.z = cvt_pk_bf16(b[0], b[1]); r.w = cvt_pk_bf16(b[2], b[3]); return r; }
;     __device__ __forceinline__ void operator()(const f32x4 (&acc)[2][2][4][2], const Unit& u, int wr, int wc, int fr, int fq) const {
;     ...
;                 const int row = row0 + ai * 128 + m * 16; const int b = row >> 13, pos = row & (SEQ - 1), pp = (pos & ~15) | p16(pos & 15);
;                 const f32x4 pa = *(const f32x4*)(sskv + (size_t)row * 8), pb = *(const f32x4*)(sskv + (size_t)row * 8 + 4);
;                 const float rs = rsqrtf((((pa[0] + pa[1]) + (pa[2] + pa[3])) + ((pb[0] + pb[1]) + (pb[2] + pb[3]))) * (1.f / 256.f) + EPS);
; #pragma unroll
;                 for (int bj = 0; bj < 2; ++bj) {
;                     const int head = 2 * u.pn + bj;
;                     const f32x4 v0 = acc[ai][bj][m][0] * rs, v1 = acc[ai][bj][m][1] * rs;
;                     if (wc < 2) {
;                         *(v4u*)(Km + (size_t)row * 768 + head * 96 + 32 * wc + 8 * fq) = pack8(v0, v1);
;                     } else {
;                         bf16* base = VmT + ((size_t)((b * 8 + head) * 64 + 32 * (wc - 2) + 8 * fq)) * SEQ + pp;
;                         const unsigned w0_ = cvt_pk_bf16(v0[0], v0[1]), w1_ = cvt_pk_bf16(v0[2], v0[3]), w2_ = cvt_pk_bf16(v1[0], v1[1]), w3_ = cvt_pk_bf16(v1[2], v1[3]);
;                         base[0] = (bf16)(w0_ & 0xffffu); base[(size_t)SEQ] = (bf16)(w0_ >> 16); base[(size_t)2 * SEQ] = (bf16)(w1_ & 0xffffu); base[(size_t)3 * SEQ] = (bf16)(w1_ >> 16);
;                         base[(size_t)4 * SEQ] = (bf16)(w2_ & 0xffffu); base[(size_t)5 * SEQ] = (bf16)(w2_ >> 16); base[(size_t)6 * SEQ] = (bf16)(w3_ & 0xffffu); base[(size_t)7 * SEQ] = (bf16)(w3_ >> 16);
.LBB0_857:
	v_readfirstlane_b32 s98, v228
	v_lshlrev_b32_e32 v235, 4, v229
	s_lshr_b32 s98, s98, 6
	s_lshl_b32 s98, s98, 10
	s_add_i32 s98, s98, 0x21000
	v_add_u32_e32 v235, s98, v235
	v_lshrrev_b32_e32 v234, 4, v229
	v_and_b32_e32 v236, 15, v229
	v_bfe_u32 v237, v236, 2, 1
	v_lshrrev_b32_e32 v238, 3, v236
	v_and_b32_e32 v236, 3, v236
	v_lshl_add_u32 v236, v237, 3, v236
	v_lshl_add_u32 v236, v238, 2, v236
	v_lshlrev_b32_e32 v236, 1, v236
	v_lshl_add_u32 v236, v234, 8, v236
	v_add_u32_e32 v234, s98, v236
	v_lshrrev_b32_e32 v237, 1, v229
	v_and_b32_e32 v238, 1, v229
	v_lshlrev_b32_e32 v238, 4, v238
	v_lshl_or_b32 v236, v237, 14, v238
	s_lshl_b32 s0, s8, 8
	s_add_i32 s0, s0, s81
	v_or_b32_e32 v144, s0, v139
	v_ashrrev_i32_e32 v145, 31, v144
	v_lshlrev_b64 v[146:147], 5, v[144:145]
	v_lshl_add_u64 v[146:147], s[82:83], 0, v[146:147]
	global_load_dwordx4 v[156:159], v[146:147], off
	global_load_dwordx4 v[160:163], v[146:147], off offset:16
	s_ashr_i32 s1, s0, 10
	s_and_b32 s0, s0, 0x1fc0
	v_or_b32_e32 v136, s0, v149
	s_lshl_b32 s49, s6, 1
	s_and_b32 s64, s1, -8
	s_mov_b64 s[8:9], -1
	s_waitcnt vmcnt(0)
	v_mov_b32_e32 v146, v156
	v_mov_b32_e32 v147, v160
	v_mov_b32_e32 v160, v157
	v_mov_b32_e32 v156, v158
	v_mov_b32_e32 v157, v162
	v_mov_b32_e32 v162, v159
	v_pk_add_f32 v[146:147], v[146:147], v[160:161]
	v_pk_add_f32 v[156:157], v[156:157], v[162:163]
	s_nop 0
	v_pk_add_f32 v[146:147], v[146:147], v[156:157]
	s_nop 0
	v_add_f32_e32 v145, v146, v147
	v_fmamk_f32 v145, v145, 0x3b800000, v154
	v_cmp_gt_f32_e32 vcc, s72, v145
	v_mul_f32_e32 v146, 0x4b800000, v145
	s_nop 0
	v_cndmask_b32_e32 v145, v145, v146, vcc
	v_rsq_f32_e32 v145, v145
	s_nop 0
	v_mul_f32_e32 v146, 0x45800000, v145
	v_cndmask_b32_e32 v146, v145, v146, vcc
	v_pk_mul_f32 v[126:127], v[126:127], v[146:147] op_sel_hi:[1,0]
	v_pk_mul_f32 v[156:157], v[124:125], v[146:147] op_sel_hi:[1,0]
	v_pk_mul_f32 v[158:159], v[122:123], v[146:147] op_sel_hi:[1,0]
	v_pk_mul_f32 v[122:123], v[120:121], v[146:147] op_sel_hi:[1,0]
	s_and_b64 vcc, exec, s[46:47]
	v_lshlrev_b32_e32 v124, 1, v136
	v_cvt_pk_bf16_f32 v120, v156, v157
	v_cvt_pk_bf16_f32 v121, v126, v127
	v_cvt_pk_bf16_f32 v122, v122, v123
	v_cvt_pk_bf16_f32 v123, v158, v159
	s_cbranch_vccz .LBB0_859
	s_add_i32 s0, s64, s49
	v_lshl_add_u32 v126, s0, 6, v150
	v_ashrrev_i32_e32 v127, 31, v126
	v_lshlrev_b64 v[126:127], 14, v[126:127]
	v_lshl_add_u64 v[126:127], s[16:17], 0, v[126:127]
	v_mov_b32_e32 v125, v137
	v_lshl_add_u64 v[126:127], v[126:127], 0, v[124:125]
	s_nop 0
	v_readfirstlane_b32 s98, v126
	v_readfirstlane_b32 s99, v127
	s_mov_b64 s[8:9], 0
	ds_write_b16 v234, v120
	ds_write_b16_d16_hi v234, v120 offset:32
	ds_write_b16 v234, v121 offset:64
	ds_write_b16_d16_hi v234, v121 offset:96
	ds_write_b16 v234, v122 offset:128
	ds_write_b16_d16_hi v234, v122 offset:160
	ds_write_b16 v234, v123 offset:192
	ds_write_b16_d16_hi v234, v123 offset:224
	ds_read_b128 v[240:243], v235
	s_waitcnt lgkmcnt(0)
	global_store_dwordx4 v236, v[240:243], s[98:99]

; __device__ __forceinline__ unsigned cvt_pk_bf16(float lo, float hi) { f32x2_t v = {lo, hi}; bf16x2_t b = __builtin_convertvector(v, bf16x2_t); return __builtin_bit_cast(unsigned, b); }
; __device__ __forceinline__ v4u pack8(f32x4 a, f32x4 b) { v4u r; r.x = cvt_pk_bf16(a[0], a[1]); r.y = cvt_pk_bf16(a[2], a[3]); r.z = cvt_pk_bf16(b[0], b[1]); r.w = cvt_pk_bf16(b[2], b[3]); return r; }
;     __device__ __forceinline__ void operator()(const f32x4 (&acc)[2][2][4][2], const Unit& u, int wr, int wc, int fr, int fq) const {
;     ...
;                 for (int bj = 0; bj < 2; ++bj) {
;                     const int head = 2 * u.pn + bj;
;                     const f32x4 v0 = acc[ai][bj][m][0] * rs, v1 = acc[ai][bj][m][1] * rs;
;                     if (wc < 2) {
;                         *(v4u*)(Km + (size_t)row * 768 + head * 96 + 32 * wc + 8 * fq) = pack8(v0, v1);
;                     } else {
;                         bf16* base = VmT + ((size_t)((b * 8 + head) * 64 + 32 * (wc - 2) + 8 * fq)) * SEQ + pp;
;                         const unsigned w0_ = cvt_pk_bf16(v0[0], v0[1]), w1_ = cvt_pk_bf16(v0[2], v0[3]), w2_ = cvt_pk_bf16(v1[0], v1[1]), w3_ = cvt_pk_bf16(v1[2], v1[3]);
;                         base[0] = (bf16)(w0_ & 0xffffu); base[(size_t)SEQ] = (bf16)(w0_ >> 16); base[(size_t)2 * SEQ] = (bf16)(w1_ & 0xffffu); base[(size_t)3 * SEQ] = (bf16)(w1_ >> 16);
;                         base[(size_t)4 * SEQ] = (bf16)(w2_ & 0xffffu); base[(size_t)5 * SEQ] = (bf16)(w2_ >> 16); base[(size_t)6 * SEQ] = (bf16)(w3_ & 0xffffu); base[(size_t)7 * SEQ] = (bf16)(w3_ >> 16);
.LBB0_861:
	v_mov_b32_e32 v147, v146
	s_nop 0
	v_mov_b32_e32 v120, v146
	v_mov_b32_e32 v121, v146
	v_pk_mul_f32 v[118:119], v[118:119], v[120:121]
	v_pk_mul_f32 v[116:117], v[116:117], v[146:147]
	v_pk_mul_f32 v[120:121], v[114:115], v[120:121]
	v_pk_mul_f32 v[114:115], v[112:113], v[146:147]
	v_cndmask_b32_e64 v112, 0, 1, s[46:47]
	v_readlane_b32 s86, v251, 2
	s_or_b32 s51, s49, 1
	s_mov_b64 s[8:9], -1
	v_cmp_ne_u32_e64 s[6:7], 1, v112
	s_andn2_b64 vcc, exec, s[46:47]
	v_cvt_pk_bf16_f32 v112, v116, v117
	v_cvt_pk_bf16_f32 v113, v118, v119
	v_cvt_pk_bf16_f32 v114, v114, v115
	v_cvt_pk_bf16_f32 v115, v120, v121
	v_readlane_b32 s87, v251, 3
	s_cbranch_vccnz .LBB0_863
	s_add_i32 s0, s64, s51
	v_lshl_add_u32 v116, s0, 6, v150
	v_ashrrev_i32_e32 v117, 31, v116
	v_lshlrev_b64 v[116:117], 14, v[116:117]
	v_lshl_add_u64 v[116:117], s[16:17], 0, v[116:117]
	v_mov_b32_e32 v125, v137
	v_lshl_add_u64 v[116:117], v[116:117], 0, v[124:125]
	s_nop 0
	v_readfirstlane_b32 s98, v116
	v_readfirstlane_b32 s99, v117
	s_mov_b64 s[8:9], 0
	ds_write_b16 v234, v112
	ds_write_b16_d16_hi v234, v112 offset:32
	ds_write_b16 v234, v113 offset:64
	ds_write_b16_d16_hi v234, v113 offset:96
	ds_write_b16 v234, v114 offset:128
	ds_write_b16_d16_hi v234, v114 offset:160
	ds_write_b16 v234, v115 offset:192
	ds_write_b16_d16_hi v234, v115 offset:224
	ds_read_b128 v[240:243], v235
	s_waitcnt lgkmcnt(0)
	global_store_dwordx4 v236, v[240:243], s[98:99]

; __device__ __forceinline__ unsigned cvt_pk_bf16(float lo, float hi) { f32x2_t v = {lo, hi}; bf16x2_t b = __builtin_convertvector(v, bf16x2_t); return __builtin_bit_cast(unsigned, b); }
; __device__ __forceinline__ int p16(int k) { return ((k >> 2) & 1) * 8 + (k >> 3) * 4 + (k & 3); }
; __device__ __forceinline__ v4u pack8(f32x4 a, f32x4 b) { v4u r; r.x = cvt_pk_bf16(a[0], a[1]); r.y = cvt_pk_bf16(a[2], a[3]); r.z = cvt_pk_bf16(b[0], b[1]); r.w = cvt_pk_bf16(b[2], b[3]); return r; }
;     __device__ __forceinline__ void operator()(const f32x4 (&acc)[2][2][4][2], const Unit& u, int wr, int wc, int fr, int fq) const {
;     ...
;                 const int row = row0 + ai * 128 + m * 16; const int b = row >> 13, pos = row & (SEQ - 1), pp = (pos & ~15) | p16(pos & 15);
;                 const f32x4 pa = *(const f32x4*)(sskv + (size_t)row * 8), pb = *(const f32x4*)(sskv + (size_t)row * 8 + 4);
;                 const float rs = rsqrtf((((pa[0] + pa[1]) + (pa[2] + pa[3])) + ((pb[0] + pb[1]) + (pb[2] + pb[3]))) * (1.f / 256.f) + EPS);
; #pragma unroll
;                 for (int bj = 0; bj < 2; ++bj) {
;                     const int head = 2 * u.pn + bj;
;                     const f32x4 v0 = acc[ai][bj][m][0] * rs, v1 = acc[ai][bj][m][1] * rs;
;                     if (wc < 2) {
;                         *(v4u*)(Km + (size_t)row * 768 + head * 96 + 32 * wc + 8 * fq) = pack8(v0, v1);
;                     } else {
;                         bf16* base = VmT + ((size_t)((b * 8 + head) * 64 + 32 * (wc - 2) + 8 * fq)) * SEQ + pp;
;                         const unsigned w0_ = cvt_pk_bf16(v0[0], v0[1]), w1_ = cvt_pk_bf16(v0[2], v0[3]), w2_ = cvt_pk_bf16(v1[0], v1[1]), w3_ = cvt_pk_bf16(v1[2], v1[3]);
;                         base[0] = (bf16)(w0_ & 0xffffu); base[(size_t)SEQ] = (bf16)(w0_ >> 16); base[(size_t)2 * SEQ] = (bf16)(w1_ & 0xffffu); base[(size_t)3 * SEQ] = (bf16)(w1_ >> 16);
;                         base[(size_t)4 * SEQ] = (bf16)(w2_ & 0xffffu); base[(size_t)5 * SEQ] = (bf16)(w2_ >> 16); base[(size_t)6 * SEQ] = (bf16)(w3_ & 0xffffu); base[(size_t)7 * SEQ] = (bf16)(w3_ >> 16);
.LBB0_865:
	s_nop 1
	v_or_b32_e32 v114, 16, v144
	v_ashrrev_i32_e32 v115, 31, v114
	v_lshlrev_b64 v[112:113], 5, v[114:115]
	v_lshl_add_u64 v[112:113], s[82:83], 0, v[112:113]
	global_load_dwordx4 v[116:119], v[112:113], off
	global_load_dwordx4 v[120:123], v[112:113], off offset:16
	v_and_or_b32 v124, v114, s84, v149
	s_mov_b64 s[8:9], -1
	s_waitcnt vmcnt(1)
	v_mov_b32_e32 v112, v116
	s_waitcnt vmcnt(0)
	v_mov_b32_e32 v113, v120
	v_mov_b32_e32 v120, v117
	v_mov_b32_e32 v116, v118
	v_mov_b32_e32 v117, v122
	v_mov_b32_e32 v122, v119
	v_pk_add_f32 v[112:113], v[112:113], v[120:121]
	v_pk_add_f32 v[116:117], v[116:117], v[122:123]
	s_nop 0
	v_pk_add_f32 v[112:113], v[112:113], v[116:117]
	s_nop 0
	v_add_f32_e32 v112, v112, v113
	v_fmamk_f32 v112, v112, 0x3b800000, v154
	v_cmp_gt_f32_e32 vcc, s72, v112
	v_mul_f32_e32 v113, 0x4b800000, v112
	s_nop 0
	v_cndmask_b32_e32 v112, v112, v113, vcc
	v_rsq_f32_e32 v112, v112
	s_nop 0
	v_mul_f32_e32 v113, 0x45800000, v112
	v_cndmask_b32_e32 v112, v112, v113, vcc
	v_pk_mul_f32 v[110:111], v[110:111], v[112:113] op_sel_hi:[1,0]
	v_pk_mul_f32 v[116:117], v[108:109], v[112:113] op_sel_hi:[1,0]
	v_pk_mul_f32 v[118:119], v[106:107], v[112:113] op_sel_hi:[1,0]
	v_pk_mul_f32 v[106:107], v[104:105], v[112:113] op_sel_hi:[1,0]
	s_and_b64 vcc, exec, s[6:7]
	v_lshlrev_b32_e32 v108, 1, v124
	v_cvt_pk_bf16_f32 v104, v116, v117
	v_cvt_pk_bf16_f32 v105, v110, v111
	v_cvt_pk_bf16_f32 v106, v106, v107
	v_cvt_pk_bf16_f32 v107, v118, v119
	s_cbranch_vccnz .LBB0_867
	s_add_i32 s0, s64, s49
	v_lshl_add_u32 v110, s0, 6, v150
	v_ashrrev_i32_e32 v111, 31, v110
	v_lshlrev_b64 v[110:111], 14, v[110:111]
	v_lshl_add_u64 v[110:111], s[16:17], 0, v[110:111]
	v_mov_b32_e32 v109, v137
	v_lshl_add_u64 v[110:111], v[110:111], 0, v[108:109]
	s_nop 0
	v_readfirstlane_b32 s98, v110
	v_readfirstlane_b32 s99, v111
	s_mov_b64 s[8:9], 0
	ds_write_b16 v234, v104
	ds_write_b16_d16_hi v234, v104 offset:32
	ds_write_b16 v234, v105 offset:64
	ds_write_b16_d16_hi v234, v105 offset:96
	ds_write_b16 v234, v106 offset:128
	ds_write_b16_d16_hi v234, v106 offset:160
	ds_write_b16 v234, v107 offset:192
	ds_write_b16_d16_hi v234, v107 offset:224
	ds_read_b128 v[240:243], v235
	s_waitcnt lgkmcnt(0)
	global_store_dwordx4 v236, v[240:243], s[98:99]

; __device__ __forceinline__ unsigned cvt_pk_bf16(float lo, float hi) { f32x2_t v = {lo, hi}; bf16x2_t b = __builtin_convertvector(v, bf16x2_t); return __builtin_bit_cast(unsigned, b); }
; __device__ __forceinline__ v4u pack8(f32x4 a, f32x4 b) { v4u r; r.x = cvt_pk_bf16(a[0], a[1]); r.y = cvt_pk_bf16(a[2], a[3]); r.z = cvt_pk_bf16(b[0], b[1]); r.w = cvt_pk_bf16(b[2], b[3]); return r; }
;     __device__ __forceinline__ void operator()(const f32x4 (&acc)[2][2][4][2], const Unit& u, int wr, int wc, int fr, int fq) const {
;     ...
;                 for (int bj = 0; bj < 2; ++bj) {
;                     const int head = 2 * u.pn + bj;
;                     const f32x4 v0 = acc[ai][bj][m][0] * rs, v1 = acc[ai][bj][m][1] * rs;
;                     if (wc < 2) {
;                         *(v4u*)(Km + (size_t)row * 768 + head * 96 + 32 * wc + 8 * fq) = pack8(v0, v1);
;                     } else {
;                         bf16* base = VmT + ((size_t)((b * 8 + head) * 64 + 32 * (wc - 2) + 8 * fq)) * SEQ + pp;
;                         const unsigned w0_ = cvt_pk_bf16(v0[0], v0[1]), w1_ = cvt_pk_bf16(v0[2], v0[3]), w2_ = cvt_pk_bf16(v1[0], v1[1]), w3_ = cvt_pk_bf16(v1[2], v1[3]);
;                         base[0] = (bf16)(w0_ & 0xffffu); base[(size_t)SEQ] = (bf16)(w0_ >> 16); base[(size_t)2 * SEQ] = (bf16)(w1_ & 0xffffu); base[(size_t)3 * SEQ] = (bf16)(w1_ >> 16);
;                         base[(size_t)4 * SEQ] = (bf16)(w2_ & 0xffffu); base[(size_t)5 * SEQ] = (bf16)(w2_ >> 16); base[(size_t)6 * SEQ] = (bf16)(w3_ & 0xffffu); base[(size_t)7 * SEQ] = (bf16)(w3_ >> 16);
.LBB0_869:
	v_mov_b32_e32 v113, v112
	s_nop 0
	v_mov_b32_e32 v104, v112
	v_mov_b32_e32 v105, v112
	v_pk_mul_f32 v[102:103], v[102:103], v[104:105]
	v_pk_mul_f32 v[100:101], v[100:101], v[112:113]
	v_pk_mul_f32 v[104:105], v[98:99], v[104:105]
	v_pk_mul_f32 v[98:99], v[96:97], v[112:113]
	s_mov_b64 s[8:9], -1
	s_and_b64 vcc, exec, s[6:7]
	v_cvt_pk_bf16_f32 v96, v100, v101
	v_cvt_pk_bf16_f32 v97, v102, v103
	v_cvt_pk_bf16_f32 v98, v98, v99
	v_cvt_pk_bf16_f32 v99, v104, v105
	s_cbranch_vccnz .LBB0_871
	s_add_i32 s0, s64, s51
	v_lshl_add_u32 v100, s0, 6, v150
	v_ashrrev_i32_e32 v101, 31, v100
	v_lshlrev_b64 v[100:101], 14, v[100:101]
	v_lshl_add_u64 v[100:101], s[16:17], 0, v[100:101]
	v_mov_b32_e32 v109, v137
	v_lshl_add_u64 v[100:101], v[100:101], 0, v[108:109]
	s_nop 0
	v_readfirstlane_b32 s98, v100
	v_readfirstlane_b32 s99, v101
	s_mov_b64 s[8:9], 0
	ds_write_b16 v234, v96
	ds_write_b16_d16_hi v234, v96 offset:32
	ds_write_b16 v234, v97 offset:64
	ds_write_b16_d16_hi v234, v97 offset:96
	ds_write_b16 v234, v98 offset:128
	ds_write_b16_d16_hi v234, v98 offset:160
	ds_write_b16 v234, v99 offset:192
	ds_write_b16_d16_hi v234, v99 offset:224
	ds_read_b128 v[240:243], v235
	s_waitcnt lgkmcnt(0)
	global_store_dwordx4 v236, v[240:243], s[98:99]

; __device__ __forceinline__ unsigned cvt_pk_bf16(float lo, float hi) { f32x2_t v = {lo, hi}; bf16x2_t b = __builtin_convertvector(v, bf16x2_t); return __builtin_bit_cast(unsigned, b); }
; __device__ __forceinline__ int p16(int k) { return ((k >> 2) & 1) * 8 + (k >> 3) * 4 + (k & 3); }
; __device__ __forceinline__ v4u pack8(f32x4 a, f32x4 b) { v4u r; r.x = cvt_pk_bf16(a[0], a[1]); r.y = cvt_pk_bf16(a[2], a[3]); r.z = cvt_pk_bf16(b[0], b[1]); r.w = cvt_pk_bf16(b[2], b[3]); return r; }
;     __device__ __forceinline__ void operator()(const f32x4 (&acc)[2][2][4][2], const Unit& u, int wr, int wc, int fr, int fq) const {
;     ...
;                 const int row = row0 + ai * 128 + m * 16; const int b = row >> 13, pos = row & (SEQ - 1), pp = (pos & ~15) | p16(pos & 15);
;                 const f32x4 pa = *(const f32x4*)(sskv + (size_t)row * 8), pb = *(const f32x4*)(sskv + (size_t)row * 8 + 4);
;                 const float rs = rsqrtf((((pa[0] + pa[1]) + (pa[2] + pa[3])) + ((pb[0] + pb[1]) + (pb[2] + pb[3]))) * (1.f / 256.f) + EPS);
; #pragma unroll
;                 for (int bj = 0; bj < 2; ++bj) {
;                     const int head = 2 * u.pn + bj;
;                     const f32x4 v0 = acc[ai][bj][m][0] * rs, v1 = acc[ai][bj][m][1] * rs;
;                     if (wc < 2) {
;                         *(v4u*)(Km + (size_t)row * 768 + head * 96 + 32 * wc + 8 * fq) = pack8(v0, v1);
;                     } else {
;                         bf16* base = VmT + ((size_t)((b * 8 + head) * 64 + 32 * (wc - 2) + 8 * fq)) * SEQ + pp;
;                         const unsigned w0_ = cvt_pk_bf16(v0[0], v0[1]), w1_ = cvt_pk_bf16(v0[2], v0[3]), w2_ = cvt_pk_bf16(v1[0], v1[1]), w3_ = cvt_pk_bf16(v1[2], v1[3]);
;                         base[0] = (bf16)(w0_ & 0xffffu); base[(size_t)SEQ] = (bf16)(w0_ >> 16); base[(size_t)2 * SEQ] = (bf16)(w1_ & 0xffffu); base[(size_t)3 * SEQ] = (bf16)(w1_ >> 16);
;                         base[(size_t)4 * SEQ] = (bf16)(w2_ & 0xffffu); base[(size_t)5 * SEQ] = (bf16)(w2_ >> 16); base[(size_t)6 * SEQ] = (bf16)(w3_ & 0xffffu); base[(size_t)7 * SEQ] = (bf16)(w3_ >> 16);
.LBB0_873:
	s_nop 1
	v_or_b32_e32 v98, 32, v144
	v_ashrrev_i32_e32 v99, 31, v98
	v_lshlrev_b64 v[96:97], 5, v[98:99]
	v_lshl_add_u64 v[96:97], s[82:83], 0, v[96:97]
	global_load_dwordx4 v[100:103], v[96:97], off
	global_load_dwordx4 v[104:107], v[96:97], off offset:16
	v_and_or_b32 v108, v98, s85, v149
	s_mov_b64 s[8:9], -1
	s_waitcnt vmcnt(1)
	v_mov_b32_e32 v96, v100
	s_waitcnt vmcnt(0)
	v_mov_b32_e32 v97, v104
	v_mov_b32_e32 v104, v101
	v_mov_b32_e32 v100, v102
	v_mov_b32_e32 v101, v106
	v_mov_b32_e32 v106, v103
	v_pk_add_f32 v[96:97], v[96:97], v[104:105]
	v_pk_add_f32 v[100:101], v[100:101], v[106:107]
	s_nop 0
	v_pk_add_f32 v[96:97], v[96:97], v[100:101]
	s_nop 0
	v_add_f32_e32 v96, v96, v97
	v_fmamk_f32 v96, v96, 0x3b800000, v154
	v_cmp_gt_f32_e32 vcc, s72, v96
	v_mul_f32_e32 v97, 0x4b800000, v96
	s_nop 0
	v_cndmask_b32_e32 v96, v96, v97, vcc
	v_rsq_f32_e32 v96, v96
	s_nop 0
	v_mul_f32_e32 v97, 0x45800000, v96
	v_cndmask_b32_e32 v96, v96, v97, vcc
	v_pk_mul_f32 v[94:95], v[94:95], v[96:97] op_sel_hi:[1,0]
	v_pk_mul_f32 v[100:101], v[92:93], v[96:97] op_sel_hi:[1,0]
	v_pk_mul_f32 v[102:103], v[90:91], v[96:97] op_sel_hi:[1,0]
	v_pk_mul_f32 v[90:91], v[88:89], v[96:97] op_sel_hi:[1,0]
	s_and_b64 vcc, exec, s[6:7]
	v_lshlrev_b32_e32 v92, 1, v108
	v_cvt_pk_bf16_f32 v88, v100, v101
	v_cvt_pk_bf16_f32 v89, v94, v95
	v_cvt_pk_bf16_f32 v90, v90, v91
	v_cvt_pk_bf16_f32 v91, v102, v103
	s_cbranch_vccnz .LBB0_875
	s_add_i32 s0, s64, s49
	v_lshl_add_u32 v94, s0, 6, v150
	v_ashrrev_i32_e32 v95, 31, v94
	v_lshlrev_b64 v[94:95], 14, v[94:95]
	v_lshl_add_u64 v[94:95], s[16:17], 0, v[94:95]
	v_mov_b32_e32 v93, v137
	v_lshl_add_u64 v[94:95], v[94:95], 0, v[92:93]
	s_nop 0
	v_readfirstlane_b32 s98, v94
	v_readfirstlane_b32 s99, v95
	s_mov_b64 s[8:9], 0
	ds_write_b16 v234, v88
	ds_write_b16_d16_hi v234, v88 offset:32
	ds_write_b16 v234, v89 offset:64
	ds_write_b16_d16_hi v234, v89 offset:96
	ds_write_b16 v234, v90 offset:128
	ds_write_b16_d16_hi v234, v90 offset:160
	ds_write_b16 v234, v91 offset:192
	ds_write_b16_d16_hi v234, v91 offset:224
	ds_read_b128 v[240:243], v235
	s_waitcnt lgkmcnt(0)
	global_store_dwordx4 v236, v[240:243], s[98:99]

; __device__ __forceinline__ unsigned cvt_pk_bf16(float lo, float hi) { f32x2_t v = {lo, hi}; bf16x2_t b = __builtin_convertvector(v, bf16x2_t); return __builtin_bit_cast(unsigned, b); }
; __device__ __forceinline__ v4u pack8(f32x4 a, f32x4 b) { v4u r; r.x = cvt_pk_bf16(a[0], a[1]); r.y = cvt_pk_bf16(a[2], a[3]); r.z = cvt_pk_bf16(b[0], b[1]); r.w = cvt_pk_bf16(b[2], b[3]); return r; }
;     __device__ __forceinline__ void operator()(const f32x4 (&acc)[2][2][4][2], const Unit& u, int wr, int wc, int fr, int fq) const {
;     ...
;                 for (int bj = 0; bj < 2; ++bj) {
;                     const int head = 2 * u.pn + bj;
;                     const f32x4 v0 = acc[ai][bj][m][0] * rs, v1 = acc[ai][bj][m][1] * rs;
;                     if (wc < 2) {
;                         *(v4u*)(Km + (size_t)row * 768 + head * 96 + 32 * wc + 8 * fq) = pack8(v0, v1);
;                     } else {
;                         bf16* base = VmT + ((size_t)((b * 8 + head) * 64 + 32 * (wc - 2) + 8 * fq)) * SEQ + pp;
;                         const unsigned w0_ = cvt_pk_bf16(v0[0], v0[1]), w1_ = cvt_pk_bf16(v0[2], v0[3]), w2_ = cvt_pk_bf16(v1[0], v1[1]), w3_ = cvt_pk_bf16(v1[2], v1[3]);
;                         base[0] = (bf16)(w0_ & 0xffffu); base[(size_t)SEQ] = (bf16)(w0_ >> 16); base[(size_t)2 * SEQ] = (bf16)(w1_ & 0xffffu); base[(size_t)3 * SEQ] = (bf16)(w1_ >> 16);
;                         base[(size_t)4 * SEQ] = (bf16)(w2_ & 0xffffu); base[(size_t)5 * SEQ] = (bf16)(w2_ >> 16); base[(size_t)6 * SEQ] = (bf16)(w3_ & 0xffffu); base[(size_t)7 * SEQ] = (bf16)(w3_ >> 16);
.LBB0_877:
	v_mov_b32_e32 v97, v96
	s_nop 0
	v_mov_b32_e32 v88, v96
	v_mov_b32_e32 v89, v96
	v_pk_mul_f32 v[86:87], v[86:87], v[88:89]
	v_pk_mul_f32 v[84:85], v[84:85], v[96:97]
	v_pk_mul_f32 v[88:89], v[82:83], v[88:89]
	v_pk_mul_f32 v[82:83], v[80:81], v[96:97]
	s_mov_b64 s[8:9], -1
	s_and_b64 vcc, exec, s[6:7]
	v_cvt_pk_bf16_f32 v80, v84, v85
	v_cvt_pk_bf16_f32 v81, v86, v87
	v_cvt_pk_bf16_f32 v82, v82, v83
	v_cvt_pk_bf16_f32 v83, v88, v89
	s_cbranch_vccnz .LBB0_879
	s_add_i32 s0, s64, s51
	v_lshl_add_u32 v84, s0, 6, v150
	v_ashrrev_i32_e32 v85, 31, v84
	v_lshlrev_b64 v[84:85], 14, v[84:85]
	v_lshl_add_u64 v[84:85], s[16:17], 0, v[84:85]
	v_mov_b32_e32 v93, v137
	v_lshl_add_u64 v[84:85], v[84:85], 0, v[92:93]
	s_nop 0
	v_readfirstlane_b32 s98, v84
	v_readfirstlane_b32 s99, v85
	s_mov_b64 s[8:9], 0
	ds_write_b16 v234, v80
	ds_write_b16_d16_hi v234, v80 offset:32
	ds_write_b16 v234, v81 offset:64
	ds_write_b16_d16_hi v234, v81 offset:96
	ds_write_b16 v234, v82 offset:128
	ds_write_b16_d16_hi v234, v82 offset:160
	ds_write_b16 v234, v83 offset:192
	ds_write_b16_d16_hi v234, v83 offset:224
	ds_read_b128 v[240:243], v235
	s_waitcnt lgkmcnt(0)
	global_store_dwordx4 v236, v[240:243], s[98:99]

; __device__ __forceinline__ unsigned cvt_pk_bf16(float lo, float hi) { f32x2_t v = {lo, hi}; bf16x2_t b = __builtin_convertvector(v, bf16x2_t); return __builtin_bit_cast(unsigned, b); }
; __device__ __forceinline__ int p16(int k) { return ((k >> 2) & 1) * 8 + (k >> 3) * 4 + (k & 3); }
; __device__ __forceinline__ v4u pack8(f32x4 a, f32x4 b) { v4u r; r.x = cvt_pk_bf16(a[0], a[1]); r.y = cvt_pk_bf16(a[2], a[3]); r.z = cvt_pk_bf16(b[0], b[1]); r.w = cvt_pk_bf16(b[2], b[3]); return r; }
;     __device__ __forceinline__ void operator()(const f32x4 (&acc)[2][2][4][2], const Unit& u, int wr, int wc, int fr, int fq) const {
;     ...
;                 const int row = row0 + ai * 128 + m * 16; const int b = row >> 13, pos = row & (SEQ - 1), pp = (pos & ~15) | p16(pos & 15);
;                 const f32x4 pa = *(const f32x4*)(sskv + (size_t)row * 8), pb = *(const f32x4*)(sskv + (size_t)row * 8 + 4);
;                 const float rs = rsqrtf((((pa[0] + pa[1]) + (pa[2] + pa[3])) + ((pb[0] + pb[1]) + (pb[2] + pb[3]))) * (1.f / 256.f) + EPS);
; #pragma unroll
;                 for (int bj = 0; bj < 2; ++bj) {
;                     const int head = 2 * u.pn + bj;
;                     const f32x4 v0 = acc[ai][bj][m][0] * rs, v1 = acc[ai][bj][m][1] * rs;
;                     if (wc < 2) {
;                         *(v4u*)(Km + (size_t)row * 768 + head * 96 + 32 * wc + 8 * fq) = pack8(v0, v1);
;                     } else {
;                         bf16* base = VmT + ((size_t)((b * 8 + head) * 64 + 32 * (wc - 2) + 8 * fq)) * SEQ + pp;
;                         const unsigned w0_ = cvt_pk_bf16(v0[0], v0[1]), w1_ = cvt_pk_bf16(v0[2], v0[3]), w2_ = cvt_pk_bf16(v1[0], v1[1]), w3_ = cvt_pk_bf16(v1[2], v1[3]);
;                         base[0] = (bf16)(w0_ & 0xffffu); base[(size_t)SEQ] = (bf16)(w0_ >> 16); base[(size_t)2 * SEQ] = (bf16)(w1_ & 0xffffu); base[(size_t)3 * SEQ] = (bf16)(w1_ >> 16);
;                         base[(size_t)4 * SEQ] = (bf16)(w2_ & 0xffffu); base[(size_t)5 * SEQ] = (bf16)(w2_ >> 16); base[(size_t)6 * SEQ] = (bf16)(w3_ & 0xffffu); base[(size_t)7 * SEQ] = (bf16)(w3_ >> 16);
.LBB0_881:
	s_nop 1
	v_or_b32_e32 v82, 48, v144
	v_ashrrev_i32_e32 v83, 31, v82
	v_lshlrev_b64 v[80:81], 5, v[82:83]
	v_lshl_add_u64 v[80:81], s[82:83], 0, v[80:81]
	global_load_dwordx4 v[84:87], v[80:81], off
	global_load_dwordx4 v[88:91], v[80:81], off offset:16
	v_and_or_b32 v92, v82, s3, v149
	s_mov_b64 s[8:9], -1
	s_waitcnt vmcnt(1)
	v_mov_b32_e32 v80, v84
	s_waitcnt vmcnt(0)
	v_mov_b32_e32 v81, v88
	v_mov_b32_e32 v88, v85
	v_mov_b32_e32 v84, v86
	v_mov_b32_e32 v85, v90
	v_mov_b32_e32 v90, v87
	v_pk_add_f32 v[80:81], v[80:81], v[88:89]
	v_pk_add_f32 v[84:85], v[84:85], v[90:91]
	s_nop 0
	v_pk_add_f32 v[80:81], v[80:81], v[84:85]
	s_nop 0
	v_add_f32_e32 v80, v80, v81
	v_fmamk_f32 v80, v80, 0x3b800000, v154
	v_cmp_gt_f32_e32 vcc, s72, v80
	v_mul_f32_e32 v81, 0x4b800000, v80
	s_nop 0
	v_cndmask_b32_e32 v80, v80, v81, vcc
	v_rsq_f32_e32 v80, v80
	s_nop 0
	v_mul_f32_e32 v81, 0x45800000, v80
	v_cndmask_b32_e32 v80, v80, v81, vcc
	v_pk_mul_f32 v[78:79], v[78:79], v[80:81] op_sel_hi:[1,0]
	v_pk_mul_f32 v[84:85], v[76:77], v[80:81] op_sel_hi:[1,0]
	v_pk_mul_f32 v[86:87], v[74:75], v[80:81] op_sel_hi:[1,0]
	v_pk_mul_f32 v[74:75], v[72:73], v[80:81] op_sel_hi:[1,0]
	s_and_b64 vcc, exec, s[6:7]
	v_lshlrev_b32_e32 v76, 1, v92
	v_cvt_pk_bf16_f32 v72, v84, v85
	v_cvt_pk_bf16_f32 v73, v78, v79
	v_cvt_pk_bf16_f32 v74, v74, v75
	v_cvt_pk_bf16_f32 v75, v86, v87
	s_cbranch_vccnz .LBB0_883
	s_add_i32 s0, s64, s49
	v_lshl_add_u32 v78, s0, 6, v150
	v_ashrrev_i32_e32 v79, 31, v78
	v_lshlrev_b64 v[78:79], 14, v[78:79]
	v_lshl_add_u64 v[78:79], s[16:17], 0, v[78:79]
	v_mov_b32_e32 v77, v137
	v_lshl_add_u64 v[78:79], v[78:79], 0, v[76:77]
	s_nop 0
	v_readfirstlane_b32 s98, v78
	v_readfirstlane_b32 s99, v79
	s_mov_b64 s[8:9], 0
	ds_write_b16 v234, v72
	ds_write_b16_d16_hi v234, v72 offset:32
	ds_write_b16 v234, v73 offset:64
	ds_write_b16_d16_hi v234, v73 offset:96
	ds_write_b16 v234, v74 offset:128
	ds_write_b16_d16_hi v234, v74 offset:160
	ds_write_b16 v234, v75 offset:192
	ds_write_b16_d16_hi v234, v75 offset:224
	ds_read_b128 v[240:243], v235
	s_waitcnt lgkmcnt(0)
	global_store_dwordx4 v236, v[240:243], s[98:99]

; __device__ __forceinline__ unsigned cvt_pk_bf16(float lo, float hi) { f32x2_t v = {lo, hi}; bf16x2_t b = __builtin_convertvector(v, bf16x2_t); return __builtin_bit_cast(unsigned, b); }
; __device__ __forceinline__ v4u pack8(f32x4 a, f32x4 b) { v4u r; r.x = cvt_pk_bf16(a[0], a[1]); r.y = cvt_pk_bf16(a[2], a[3]); r.z = cvt_pk_bf16(b[0], b[1]); r.w = cvt_pk_bf16(b[2], b[3]); return r; }
;     __device__ __forceinline__ void operator()(const f32x4 (&acc)[2][2][4][2], const Unit& u, int wr, int wc, int fr, int fq) const {
;     ...
;                 for (int bj = 0; bj < 2; ++bj) {
;                     const int head = 2 * u.pn + bj;
;                     const f32x4 v0 = acc[ai][bj][m][0] * rs, v1 = acc[ai][bj][m][1] * rs;
;                     if (wc < 2) {
;                         *(v4u*)(Km + (size_t)row * 768 + head * 96 + 32 * wc + 8 * fq) = pack8(v0, v1);
;                     } else {
;                         bf16* base = VmT + ((size_t)((b * 8 + head) * 64 + 32 * (wc - 2) + 8 * fq)) * SEQ + pp;
;                         const unsigned w0_ = cvt_pk_bf16(v0[0], v0[1]), w1_ = cvt_pk_bf16(v0[2], v0[3]), w2_ = cvt_pk_bf16(v1[0], v1[1]), w3_ = cvt_pk_bf16(v1[2], v1[3]);
;                         base[0] = (bf16)(w0_ & 0xffffu); base[(size_t)SEQ] = (bf16)(w0_ >> 16); base[(size_t)2 * SEQ] = (bf16)(w1_ & 0xffffu); base[(size_t)3 * SEQ] = (bf16)(w1_ >> 16);
;                         base[(size_t)4 * SEQ] = (bf16)(w2_ & 0xffffu); base[(size_t)5 * SEQ] = (bf16)(w2_ >> 16); base[(size_t)6 * SEQ] = (bf16)(w3_ & 0xffffu); base[(size_t)7 * SEQ] = (bf16)(w3_ >> 16);
.LBB0_885:
	v_mov_b32_e32 v81, v80
	s_nop 0
	v_mov_b32_e32 v72, v80
	v_mov_b32_e32 v73, v80
	v_pk_mul_f32 v[70:71], v[70:71], v[72:73]
	v_pk_mul_f32 v[68:69], v[68:69], v[80:81]
	v_pk_mul_f32 v[72:73], v[66:67], v[72:73]
	v_pk_mul_f32 v[66:67], v[64:65], v[80:81]
	s_mov_b64 s[8:9], -1
	s_and_b64 vcc, exec, s[6:7]
	v_cvt_pk_bf16_f32 v64, v68, v69
	v_cvt_pk_bf16_f32 v65, v70, v71
	v_cvt_pk_bf16_f32 v66, v66, v67
	v_cvt_pk_bf16_f32 v67, v72, v73
	s_cbranch_vccnz .LBB0_887
	s_add_i32 s64, s64, s51
	v_lshl_add_u32 v68, s64, 6, v150
	v_ashrrev_i32_e32 v69, 31, v68
	v_lshlrev_b64 v[68:69], 14, v[68:69]
	v_lshl_add_u64 v[68:69], s[16:17], 0, v[68:69]
	v_mov_b32_e32 v77, v137
	v_lshl_add_u64 v[68:69], v[68:69], 0, v[76:77]
	s_nop 0
	v_readfirstlane_b32 s98, v68
	v_readfirstlane_b32 s99, v69
	s_mov_b64 s[8:9], 0
	ds_write_b16 v234, v64
	ds_write_b16_d16_hi v234, v64 offset:32
	ds_write_b16 v234, v65 offset:64
	ds_write_b16_d16_hi v234, v65 offset:96
	ds_write_b16 v234, v66 offset:128
	ds_write_b16_d16_hi v234, v66 offset:160
	ds_write_b16 v234, v67 offset:192
	ds_write_b16_d16_hi v234, v67 offset:224
	ds_read_b128 v[240:243], v235
	s_waitcnt lgkmcnt(0)
	global_store_dwordx4 v236, v[240:243], s[98:99]

; __device__ __forceinline__ unsigned cvt_pk_bf16(float lo, float hi) { f32x2_t v = {lo, hi}; bf16x2_t b = __builtin_convertvector(v, bf16x2_t); return __builtin_bit_cast(unsigned, b); }
; __device__ __forceinline__ int p16(int k) { return ((k >> 2) & 1) * 8 + (k >> 3) * 4 + (k & 3); }
; __device__ __forceinline__ v4u pack8(f32x4 a, f32x4 b) { v4u r; r.x = cvt_pk_bf16(a[0], a[1]); r.y = cvt_pk_bf16(a[2], a[3]); r.z = cvt_pk_bf16(b[0], b[1]); r.w = cvt_pk_bf16(b[2], b[3]); return r; }
;     __device__ __forceinline__ void operator()(const f32x4 (&acc)[2][2][4][2], const Unit& u, int wr, int wc, int fr, int fq) const {
;     ...
;                 const int row = row0 + ai * 128 + m * 16; const int b = row >> 13, pos = row & (SEQ - 1), pp = (pos & ~15) | p16(pos & 15);
;                 const f32x4 pa = *(const f32x4*)(sskv + (size_t)row * 8), pb = *(const f32x4*)(sskv + (size_t)row * 8 + 4);
;                 const float rs = rsqrtf((((pa[0] + pa[1]) + (pa[2] + pa[3])) + ((pb[0] + pb[1]) + (pb[2] + pb[3]))) * (1.f / 256.f) + EPS);
; #pragma unroll
;                 for (int bj = 0; bj < 2; ++bj) {
;                     const int head = 2 * u.pn + bj;
;                     const f32x4 v0 = acc[ai][bj][m][0] * rs, v1 = acc[ai][bj][m][1] * rs;
;                     if (wc < 2) {
;                         *(v4u*)(Km + (size_t)row * 768 + head * 96 + 32 * wc + 8 * fq) = pack8(v0, v1);
;                     } else {
;                         bf16* base = VmT + ((size_t)((b * 8 + head) * 64 + 32 * (wc - 2) + 8 * fq)) * SEQ + pp;
;                         const unsigned w0_ = cvt_pk_bf16(v0[0], v0[1]), w1_ = cvt_pk_bf16(v0[2], v0[3]), w2_ = cvt_pk_bf16(v1[0], v1[1]), w3_ = cvt_pk_bf16(v1[2], v1[3]);
;                         base[0] = (bf16)(w0_ & 0xffffu); base[(size_t)SEQ] = (bf16)(w0_ >> 16); base[(size_t)2 * SEQ] = (bf16)(w1_ & 0xffffu); base[(size_t)3 * SEQ] = (bf16)(w1_ >> 16);
;                         base[(size_t)4 * SEQ] = (bf16)(w2_ & 0xffffu); base[(size_t)5 * SEQ] = (bf16)(w2_ >> 16); base[(size_t)6 * SEQ] = (bf16)(w3_ & 0xffffu); base[(size_t)7 * SEQ] = (bf16)(w3_ >> 16);
.LBB0_889:
	s_nop 1
	v_add_u32_e32 v64, 0x80, v144
	v_ashrrev_i32_e32 v65, 10, v64
	v_and_b32_e32 v68, -8, v65
	v_ashrrev_i32_e32 v65, 31, v64
	v_lshlrev_b64 v[66:67], 5, v[64:65]
	v_lshl_add_u64 v[66:67], s[82:83], 0, v[66:67]
	global_load_dwordx4 v[70:73], v[66:67], off
	global_load_dwordx4 v[74:77], v[66:67], off offset:16
	s_movk_i32 s0, 0x1fc0
	v_and_or_b32 v69, v64, s0, v149
	s_mov_b64 s[8:9], -1
	s_waitcnt vmcnt(1)
	v_mov_b32_e32 v66, v70
	s_waitcnt vmcnt(0)
	v_mov_b32_e32 v67, v74
	v_mov_b32_e32 v74, v71
	v_mov_b32_e32 v70, v72
	v_mov_b32_e32 v71, v76
	v_mov_b32_e32 v76, v73
	v_pk_add_f32 v[66:67], v[66:67], v[74:75]
	v_pk_add_f32 v[70:71], v[70:71], v[76:77]
	s_nop 0
	v_pk_add_f32 v[66:67], v[66:67], v[70:71]
	s_nop 0
	v_add_f32_e32 v65, v66, v67
	v_fmamk_f32 v65, v65, 0x3b800000, v154
	v_cmp_gt_f32_e32 vcc, s72, v65
	v_mul_f32_e32 v66, 0x4b800000, v65
	s_nop 0
	v_cndmask_b32_e32 v65, v65, v66, vcc
	v_rsq_f32_e32 v65, v65
	s_nop 0
	v_mul_f32_e32 v66, 0x45800000, v65
	v_cndmask_b32_e32 v66, v65, v66, vcc
	v_pk_mul_f32 v[70:71], v[62:63], v[66:67] op_sel_hi:[1,0]
	v_pk_mul_f32 v[72:73], v[60:61], v[66:67] op_sel_hi:[1,0]
	v_pk_mul_f32 v[74:75], v[58:59], v[66:67] op_sel_hi:[1,0]
	v_pk_mul_f32 v[58:59], v[56:57], v[66:67] op_sel_hi:[1,0]
	v_add_u32_e32 v56, s49, v68
	s_and_b64 vcc, exec, s[6:7]
	v_lshl_add_u32 v60, v56, 6, v150
	v_lshlrev_b32_e32 v62, 1, v69
	v_cvt_pk_bf16_f32 v56, v72, v73
	v_cvt_pk_bf16_f32 v57, v70, v71
	v_cvt_pk_bf16_f32 v58, v58, v59
	v_cvt_pk_bf16_f32 v59, v74, v75
	s_cbranch_vccnz .LBB0_891
	v_ashrrev_i32_e32 v61, 31, v60
	v_lshlrev_b64 v[70:71], 14, v[60:61]
	v_lshl_add_u64 v[70:71], s[16:17], 0, v[70:71]
	v_mov_b32_e32 v63, v137
	v_lshl_add_u64 v[70:71], v[70:71], 0, v[62:63]
	s_nop 0
	v_readfirstlane_b32 s98, v70
	v_readfirstlane_b32 s99, v71
	s_mov_b64 s[8:9], 0
	ds_write_b16 v234, v56
	ds_write_b16_d16_hi v234, v56 offset:32
	ds_write_b16 v234, v57 offset:64
	ds_write_b16_d16_hi v234, v57 offset:96
	ds_write_b16 v234, v58 offset:128
	ds_write_b16_d16_hi v234, v58 offset:160
	ds_write_b16 v234, v59 offset:192
	ds_write_b16_d16_hi v234, v59 offset:224
	ds_read_b128 v[240:243], v235
	s_waitcnt lgkmcnt(0)
	global_store_dwordx4 v236, v[240:243], s[98:99]

; __device__ __forceinline__ unsigned cvt_pk_bf16(float lo, float hi) { f32x2_t v = {lo, hi}; bf16x2_t b = __builtin_convertvector(v, bf16x2_t); return __builtin_bit_cast(unsigned, b); }
; __device__ __forceinline__ v4u pack8(f32x4 a, f32x4 b) { v4u r; r.x = cvt_pk_bf16(a[0], a[1]); r.y = cvt_pk_bf16(a[2], a[3]); r.z = cvt_pk_bf16(b[0], b[1]); r.w = cvt_pk_bf16(b[2], b[3]); return r; }
;     __device__ __forceinline__ void operator()(const f32x4 (&acc)[2][2][4][2], const Unit& u, int wr, int wc, int fr, int fq) const {
;     ...
;                 for (int bj = 0; bj < 2; ++bj) {
;                     const int head = 2 * u.pn + bj;
;                     const f32x4 v0 = acc[ai][bj][m][0] * rs, v1 = acc[ai][bj][m][1] * rs;
;                     if (wc < 2) {
;                         *(v4u*)(Km + (size_t)row * 768 + head * 96 + 32 * wc + 8 * fq) = pack8(v0, v1);
;                     } else {
;                         bf16* base = VmT + ((size_t)((b * 8 + head) * 64 + 32 * (wc - 2) + 8 * fq)) * SEQ + pp;
;                         const unsigned w0_ = cvt_pk_bf16(v0[0], v0[1]), w1_ = cvt_pk_bf16(v0[2], v0[3]), w2_ = cvt_pk_bf16(v1[0], v1[1]), w3_ = cvt_pk_bf16(v1[2], v1[3]);
;                         base[0] = (bf16)(w0_ & 0xffffu); base[(size_t)SEQ] = (bf16)(w0_ >> 16); base[(size_t)2 * SEQ] = (bf16)(w1_ & 0xffffu); base[(size_t)3 * SEQ] = (bf16)(w1_ >> 16);
;                         base[(size_t)4 * SEQ] = (bf16)(w2_ & 0xffffu); base[(size_t)5 * SEQ] = (bf16)(w2_ >> 16); base[(size_t)6 * SEQ] = (bf16)(w3_ & 0xffffu); base[(size_t)7 * SEQ] = (bf16)(w3_ >> 16);
.LBB0_893:
	v_mov_b32_e32 v67, v66
	s_nop 0
	v_mov_b32_e32 v56, v66
	v_mov_b32_e32 v57, v66
	v_pk_mul_f32 v[54:55], v[54:55], v[56:57]
	v_pk_mul_f32 v[58:59], v[52:53], v[66:67]
	v_pk_mul_f32 v[56:57], v[50:51], v[56:57]
	v_pk_mul_f32 v[50:51], v[48:49], v[66:67]
	v_add_u32_e32 v48, s51, v68
	s_mov_b64 s[8:9], -1
	s_and_b64 vcc, exec, s[6:7]
	v_lshl_add_u32 v52, v48, 6, v150
	v_cvt_pk_bf16_f32 v48, v58, v59
	v_cvt_pk_bf16_f32 v49, v54, v55
	v_cvt_pk_bf16_f32 v50, v50, v51
	v_cvt_pk_bf16_f32 v51, v56, v57
	s_cbranch_vccnz .LBB0_895
	v_ashrrev_i32_e32 v53, 31, v52
	v_lshlrev_b64 v[54:55], 14, v[52:53]
	v_lshl_add_u64 v[54:55], s[16:17], 0, v[54:55]
	v_mov_b32_e32 v63, v137
	v_lshl_add_u64 v[54:55], v[54:55], 0, v[62:63]
	s_nop 0
	v_readfirstlane_b32 s98, v54
	v_readfirstlane_b32 s99, v55
	s_mov_b64 s[8:9], 0
	ds_write_b16 v234, v48
	ds_write_b16_d16_hi v234, v48 offset:32
	ds_write_b16 v234, v49 offset:64
	ds_write_b16_d16_hi v234, v49 offset:96
	ds_write_b16 v234, v50 offset:128
	ds_write_b16_d16_hi v234, v50 offset:160
	ds_write_b16 v234, v51 offset:192
	ds_write_b16_d16_hi v234, v51 offset:224
	ds_read_b128 v[240:243], v235
	s_waitcnt lgkmcnt(0)
	global_store_dwordx4 v236, v[240:243], s[98:99]

; __device__ __forceinline__ unsigned cvt_pk_bf16(float lo, float hi) { f32x2_t v = {lo, hi}; bf16x2_t b = __builtin_convertvector(v, bf16x2_t); return __builtin_bit_cast(unsigned, b); }
; __device__ __forceinline__ int p16(int k) { return ((k >> 2) & 1) * 8 + (k >> 3) * 4 + (k & 3); }
; __device__ __forceinline__ v4u pack8(f32x4 a, f32x4 b) { v4u r; r.x = cvt_pk_bf16(a[0], a[1]); r.y = cvt_pk_bf16(a[2], a[3]); r.z = cvt_pk_bf16(b[0], b[1]); r.w = cvt_pk_bf16(b[2], b[3]); return r; }
;     __device__ __forceinline__ void operator()(const f32x4 (&acc)[2][2][4][2], const Unit& u, int wr, int wc, int fr, int fq) const {
;     ...
;                 const int row = row0 + ai * 128 + m * 16; const int b = row >> 13, pos = row & (SEQ - 1), pp = (pos & ~15) | p16(pos & 15);
;                 const f32x4 pa = *(const f32x4*)(sskv + (size_t)row * 8), pb = *(const f32x4*)(sskv + (size_t)row * 8 + 4);
;                 const float rs = rsqrtf((((pa[0] + pa[1]) + (pa[2] + pa[3])) + ((pb[0] + pb[1]) + (pb[2] + pb[3]))) * (1.f / 256.f) + EPS);
; #pragma unroll
;                 for (int bj = 0; bj < 2; ++bj) {
;                     const int head = 2 * u.pn + bj;
;                     const f32x4 v0 = acc[ai][bj][m][0] * rs, v1 = acc[ai][bj][m][1] * rs;
;                     if (wc < 2) {
;                         *(v4u*)(Km + (size_t)row * 768 + head * 96 + 32 * wc + 8 * fq) = pack8(v0, v1);
;                     } else {
;                         bf16* base = VmT + ((size_t)((b * 8 + head) * 64 + 32 * (wc - 2) + 8 * fq)) * SEQ + pp;
;                         const unsigned w0_ = cvt_pk_bf16(v0[0], v0[1]), w1_ = cvt_pk_bf16(v0[2], v0[3]), w2_ = cvt_pk_bf16(v1[0], v1[1]), w3_ = cvt_pk_bf16(v1[2], v1[3]);
;                         base[0] = (bf16)(w0_ & 0xffffu); base[(size_t)SEQ] = (bf16)(w0_ >> 16); base[(size_t)2 * SEQ] = (bf16)(w1_ & 0xffffu); base[(size_t)3 * SEQ] = (bf16)(w1_ >> 16);
;                         base[(size_t)4 * SEQ] = (bf16)(w2_ & 0xffffu); base[(size_t)5 * SEQ] = (bf16)(w2_ >> 16); base[(size_t)6 * SEQ] = (bf16)(w3_ & 0xffffu); base[(size_t)7 * SEQ] = (bf16)(w3_ >> 16);
.LBB0_897:
	s_nop 1
	v_add_u32_e32 v50, 0x90, v144
	v_ashrrev_i32_e32 v51, 31, v50
	v_lshlrev_b64 v[48:49], 5, v[50:51]
	v_lshl_add_u64 v[48:49], s[82:83], 0, v[48:49]
	global_load_dwordx4 v[54:57], v[48:49], off
	global_load_dwordx4 v[62:65], v[48:49], off offset:16
	v_and_or_b32 v53, v50, s84, v149
	s_mov_b64 s[8:9], -1
	s_waitcnt vmcnt(1)
	v_mov_b32_e32 v48, v54
	s_waitcnt vmcnt(0)
	v_mov_b32_e32 v49, v62
	v_mov_b32_e32 v62, v55
	v_mov_b32_e32 v54, v56
	v_mov_b32_e32 v55, v64
	v_mov_b32_e32 v64, v57
	v_pk_add_f32 v[48:49], v[48:49], v[62:63]
	v_pk_add_f32 v[54:55], v[54:55], v[64:65]
	s_nop 0
	v_pk_add_f32 v[48:49], v[48:49], v[54:55]
	s_nop 0
	v_add_f32_e32 v48, v48, v49
	v_fmamk_f32 v48, v48, 0x3b800000, v154
	v_cmp_gt_f32_e32 vcc, s72, v48
	v_mul_f32_e32 v49, 0x4b800000, v48
	s_nop 0
	v_cndmask_b32_e32 v48, v48, v49, vcc
	v_rsq_f32_e32 v48, v48
	s_nop 0
	v_mul_f32_e32 v49, 0x45800000, v48
	v_cndmask_b32_e32 v48, v48, v49, vcc
	v_pk_mul_f32 v[46:47], v[46:47], v[48:49] op_sel_hi:[1,0]
	v_pk_mul_f32 v[54:55], v[44:45], v[48:49] op_sel_hi:[1,0]
	v_pk_mul_f32 v[56:57], v[42:43], v[48:49] op_sel_hi:[1,0]
	v_pk_mul_f32 v[42:43], v[40:41], v[48:49] op_sel_hi:[1,0]
	s_and_b64 vcc, exec, s[6:7]
	v_lshlrev_b32_e32 v44, 1, v53
	v_cvt_pk_bf16_f32 v40, v54, v55
	v_cvt_pk_bf16_f32 v41, v46, v47
	v_cvt_pk_bf16_f32 v42, v42, v43
	v_cvt_pk_bf16_f32 v43, v56, v57
	s_cbranch_vccnz .LBB0_899
	v_ashrrev_i32_e32 v61, 31, v60
	v_lshlrev_b64 v[46:47], 14, v[60:61]
	v_lshl_add_u64 v[46:47], s[16:17], 0, v[46:47]
	v_mov_b32_e32 v45, v137
	v_lshl_add_u64 v[46:47], v[46:47], 0, v[44:45]
	s_nop 0
	v_readfirstlane_b32 s98, v46
	v_readfirstlane_b32 s99, v47
	s_mov_b64 s[8:9], 0
	ds_write_b16 v234, v40
	ds_write_b16_d16_hi v234, v40 offset:32
	ds_write_b16 v234, v41 offset:64
	ds_write_b16_d16_hi v234, v41 offset:96
	ds_write_b16 v234, v42 offset:128
	ds_write_b16_d16_hi v234, v42 offset:160
	ds_write_b16 v234, v43 offset:192
	ds_write_b16_d16_hi v234, v43 offset:224
	ds_read_b128 v[240:243], v235
	s_waitcnt lgkmcnt(0)
	global_store_dwordx4 v236, v[240:243], s[98:99]

; __device__ __forceinline__ unsigned cvt_pk_bf16(float lo, float hi) { f32x2_t v = {lo, hi}; bf16x2_t b = __builtin_convertvector(v, bf16x2_t); return __builtin_bit_cast(unsigned, b); }
; __device__ __forceinline__ v4u pack8(f32x4 a, f32x4 b) { v4u r; r.x = cvt_pk_bf16(a[0], a[1]); r.y = cvt_pk_bf16(a[2], a[3]); r.z = cvt_pk_bf16(b[0], b[1]); r.w = cvt_pk_bf16(b[2], b[3]); return r; }
;     __device__ __forceinline__ void operator()(const f32x4 (&acc)[2][2][4][2], const Unit& u, int wr, int wc, int fr, int fq) const {
;     ...
;                 for (int bj = 0; bj < 2; ++bj) {
;                     const int head = 2 * u.pn + bj;
;                     const f32x4 v0 = acc[ai][bj][m][0] * rs, v1 = acc[ai][bj][m][1] * rs;
;                     if (wc < 2) {
;                         *(v4u*)(Km + (size_t)row * 768 + head * 96 + 32 * wc + 8 * fq) = pack8(v0, v1);
;                     } else {
;                         bf16* base = VmT + ((size_t)((b * 8 + head) * 64 + 32 * (wc - 2) + 8 * fq)) * SEQ + pp;
;                         const unsigned w0_ = cvt_pk_bf16(v0[0], v0[1]), w1_ = cvt_pk_bf16(v0[2], v0[3]), w2_ = cvt_pk_bf16(v1[0], v1[1]), w3_ = cvt_pk_bf16(v1[2], v1[3]);
;                         base[0] = (bf16)(w0_ & 0xffffu); base[(size_t)SEQ] = (bf16)(w0_ >> 16); base[(size_t)2 * SEQ] = (bf16)(w1_ & 0xffffu); base[(size_t)3 * SEQ] = (bf16)(w1_ >> 16);
;                         base[(size_t)4 * SEQ] = (bf16)(w2_ & 0xffffu); base[(size_t)5 * SEQ] = (bf16)(w2_ >> 16); base[(size_t)6 * SEQ] = (bf16)(w3_ & 0xffffu); base[(size_t)7 * SEQ] = (bf16)(w3_ >> 16);
.LBB0_901:
	v_mov_b32_e32 v49, v48
	s_nop 0
	v_mov_b32_e32 v40, v48
	v_mov_b32_e32 v41, v48
	v_pk_mul_f32 v[38:39], v[38:39], v[40:41]
	v_pk_mul_f32 v[36:37], v[36:37], v[48:49]
	v_pk_mul_f32 v[40:41], v[34:35], v[40:41]
	v_pk_mul_f32 v[34:35], v[32:33], v[48:49]
	s_mov_b64 s[8:9], -1
	s_and_b64 vcc, exec, s[6:7]
	v_cvt_pk_bf16_f32 v32, v36, v37
	v_cvt_pk_bf16_f32 v33, v38, v39
	v_cvt_pk_bf16_f32 v34, v34, v35
	v_cvt_pk_bf16_f32 v35, v40, v41
	s_cbranch_vccnz .LBB0_903
	v_ashrrev_i32_e32 v53, 31, v52
	v_lshlrev_b64 v[36:37], 14, v[52:53]
	v_lshl_add_u64 v[36:37], s[16:17], 0, v[36:37]
	v_mov_b32_e32 v45, v137
	v_lshl_add_u64 v[36:37], v[36:37], 0, v[44:45]
	s_nop 0
	v_readfirstlane_b32 s98, v36
	v_readfirstlane_b32 s99, v37
	s_mov_b64 s[8:9], 0
	ds_write_b16 v234, v32
	ds_write_b16_d16_hi v234, v32 offset:32
	ds_write_b16 v234, v33 offset:64
	ds_write_b16_d16_hi v234, v33 offset:96
	ds_write_b16 v234, v34 offset:128
	ds_write_b16_d16_hi v234, v34 offset:160
	ds_write_b16 v234, v35 offset:192
	ds_write_b16_d16_hi v234, v35 offset:224
	ds_read_b128 v[240:243], v235
	s_waitcnt lgkmcnt(0)
	global_store_dwordx4 v236, v[240:243], s[98:99]

; __device__ __forceinline__ unsigned cvt_pk_bf16(float lo, float hi) { f32x2_t v = {lo, hi}; bf16x2_t b = __builtin_convertvector(v, bf16x2_t); return __builtin_bit_cast(unsigned, b); }
; __device__ __forceinline__ int p16(int k) { return ((k >> 2) & 1) * 8 + (k >> 3) * 4 + (k & 3); }
; __device__ __forceinline__ v4u pack8(f32x4 a, f32x4 b) { v4u r; r.x = cvt_pk_bf16(a[0], a[1]); r.y = cvt_pk_bf16(a[2], a[3]); r.z = cvt_pk_bf16(b[0], b[1]); r.w = cvt_pk_bf16(b[2], b[3]); return r; }
;     __device__ __forceinline__ void operator()(const f32x4 (&acc)[2][2][4][2], const Unit& u, int wr, int wc, int fr, int fq) const {
;     ...
;                 const int row = row0 + ai * 128 + m * 16; const int b = row >> 13, pos = row & (SEQ - 1), pp = (pos & ~15) | p16(pos & 15);
;                 const f32x4 pa = *(const f32x4*)(sskv + (size_t)row * 8), pb = *(const f32x4*)(sskv + (size_t)row * 8 + 4);
;                 const float rs = rsqrtf((((pa[0] + pa[1]) + (pa[2] + pa[3])) + ((pb[0] + pb[1]) + (pb[2] + pb[3]))) * (1.f / 256.f) + EPS);
; #pragma unroll
;                 for (int bj = 0; bj < 2; ++bj) {
;                     const int head = 2 * u.pn + bj;
;                     const f32x4 v0 = acc[ai][bj][m][0] * rs, v1 = acc[ai][bj][m][1] * rs;
;                     if (wc < 2) {
;                         *(v4u*)(Km + (size_t)row * 768 + head * 96 + 32 * wc + 8 * fq) = pack8(v0, v1);
;                     } else {
;                         bf16* base = VmT + ((size_t)((b * 8 + head) * 64 + 32 * (wc - 2) + 8 * fq)) * SEQ + pp;
;                         const unsigned w0_ = cvt_pk_bf16(v0[0], v0[1]), w1_ = cvt_pk_bf16(v0[2], v0[3]), w2_ = cvt_pk_bf16(v1[0], v1[1]), w3_ = cvt_pk_bf16(v1[2], v1[3]);
;                         base[0] = (bf16)(w0_ & 0xffffu); base[(size_t)SEQ] = (bf16)(w0_ >> 16); base[(size_t)2 * SEQ] = (bf16)(w1_ & 0xffffu); base[(size_t)3 * SEQ] = (bf16)(w1_ >> 16);
;                         base[(size_t)4 * SEQ] = (bf16)(w2_ & 0xffffu); base[(size_t)5 * SEQ] = (bf16)(w2_ >> 16); base[(size_t)6 * SEQ] = (bf16)(w3_ & 0xffffu); base[(size_t)7 * SEQ] = (bf16)(w3_ >> 16);
.LBB0_905:
	s_nop 1
	v_add_u32_e32 v32, 0xa0, v144
	v_ashrrev_i32_e32 v33, 31, v32
	v_lshlrev_b64 v[34:35], 5, v[32:33]
	v_lshl_add_u64 v[38:39], s[82:83], 0, v[34:35]
	global_load_dwordx4 v[34:37], v[38:39], off
	s_nop 0
	global_load_dwordx4 v[38:41], v[38:39], off offset:16
	s_mov_b64 s[64:65], -1
	s_and_b64 vcc, exec, s[6:7]
	s_waitcnt vmcnt(1)
	v_mov_b32_e32 v42, v34
	s_waitcnt vmcnt(0)
	v_mov_b32_e32 v43, v38
	v_mov_b32_e32 v38, v35
	v_mov_b32_e32 v34, v36
	v_mov_b32_e32 v35, v40
	v_mov_b32_e32 v40, v37
	v_pk_add_f32 v[36:37], v[42:43], v[38:39]
	v_pk_add_f32 v[34:35], v[34:35], v[40:41]
	s_nop 0
	v_pk_add_f32 v[34:35], v[36:37], v[34:35]
	s_nop 0
	v_add_f32_e32 v33, v34, v35
	v_fmamk_f32 v33, v33, 0x3b800000, v154
	v_mul_f32_e32 v34, 0x4b800000, v33
	v_cmp_gt_f32_e64 s[8:9], s72, v33
	s_nop 1
	v_cndmask_b32_e64 v33, v33, v34, s[8:9]
	v_rsq_f32_e32 v33, v33
	v_and_or_b32 v34, v32, s85, v149
	v_lshlrev_b32_e32 v34, 1, v34
	v_mul_f32_e32 v35, 0x45800000, v33
	v_cndmask_b32_e64 v36, v33, v35, s[8:9]
	v_pk_mul_f32 v[30:31], v[30:31], v[36:37] op_sel_hi:[1,0]
	v_pk_mul_f32 v[28:29], v[28:29], v[36:37] op_sel_hi:[1,0]
	v_pk_mul_f32 v[38:39], v[26:27], v[36:37] op_sel_hi:[1,0]
	v_pk_mul_f32 v[26:27], v[24:25], v[36:37] op_sel_hi:[1,0]
	v_cvt_pk_bf16_f32 v24, v28, v29
	v_cvt_pk_bf16_f32 v25, v30, v31
	v_cvt_pk_bf16_f32 v26, v26, v27
	v_cvt_pk_bf16_f32 v27, v38, v39
	s_cbranch_vccnz .LBB0_907
	v_ashrrev_i32_e32 v61, 31, v60
	v_lshlrev_b64 v[28:29], 14, v[60:61]
	v_lshl_add_u64 v[28:29], s[16:17], 0, v[28:29]
	v_mov_b32_e32 v35, v137
	v_lshl_add_u64 v[28:29], v[28:29], 0, v[34:35]
	s_nop 0
	v_readfirstlane_b32 s98, v28
	v_readfirstlane_b32 s99, v29
	s_mov_b64 s[64:65], 0
	ds_write_b16 v234, v24
	ds_write_b16_d16_hi v234, v24 offset:32
	ds_write_b16 v234, v25 offset:64
	ds_write_b16_d16_hi v234, v25 offset:96
	ds_write_b16 v234, v26 offset:128
	ds_write_b16_d16_hi v234, v26 offset:160
	ds_write_b16 v234, v27 offset:192
	ds_write_b16_d16_hi v234, v27 offset:224
	ds_read_b128 v[240:243], v235
	s_waitcnt lgkmcnt(0)
	global_store_dwordx4 v236, v[240:243], s[98:99]

; __device__ __forceinline__ unsigned cvt_pk_bf16(float lo, float hi) { f32x2_t v = {lo, hi}; bf16x2_t b = __builtin_convertvector(v, bf16x2_t); return __builtin_bit_cast(unsigned, b); }
; __device__ __forceinline__ v4u pack8(f32x4 a, f32x4 b) { v4u r; r.x = cvt_pk_bf16(a[0], a[1]); r.y = cvt_pk_bf16(a[2], a[3]); r.z = cvt_pk_bf16(b[0], b[1]); r.w = cvt_pk_bf16(b[2], b[3]); return r; }
;     __device__ __forceinline__ void operator()(const f32x4 (&acc)[2][2][4][2], const Unit& u, int wr, int wc, int fr, int fq) const {
;     ...
;                 for (int bj = 0; bj < 2; ++bj) {
;                     const int head = 2 * u.pn + bj;
;                     const f32x4 v0 = acc[ai][bj][m][0] * rs, v1 = acc[ai][bj][m][1] * rs;
;                     if (wc < 2) {
;                         *(v4u*)(Km + (size_t)row * 768 + head * 96 + 32 * wc + 8 * fq) = pack8(v0, v1);
;                     } else {
;                         bf16* base = VmT + ((size_t)((b * 8 + head) * 64 + 32 * (wc - 2) + 8 * fq)) * SEQ + pp;
;                         const unsigned w0_ = cvt_pk_bf16(v0[0], v0[1]), w1_ = cvt_pk_bf16(v0[2], v0[3]), w2_ = cvt_pk_bf16(v1[0], v1[1]), w3_ = cvt_pk_bf16(v1[2], v1[3]);
;                         base[0] = (bf16)(w0_ & 0xffffu); base[(size_t)SEQ] = (bf16)(w0_ >> 16); base[(size_t)2 * SEQ] = (bf16)(w1_ & 0xffffu); base[(size_t)3 * SEQ] = (bf16)(w1_ >> 16);
;                         base[(size_t)4 * SEQ] = (bf16)(w2_ & 0xffffu); base[(size_t)5 * SEQ] = (bf16)(w2_ >> 16); base[(size_t)6 * SEQ] = (bf16)(w3_ & 0xffffu); base[(size_t)7 * SEQ] = (bf16)(w3_ >> 16);
.LBB0_909:
	v_mov_b32_e32 v37, v36
	s_nop 0
	v_mov_b32_e32 v24, v36
	v_mov_b32_e32 v25, v36
	v_pk_mul_f32 v[22:23], v[22:23], v[24:25]
	v_pk_mul_f32 v[20:21], v[20:21], v[36:37]
	v_pk_mul_f32 v[24:25], v[18:19], v[24:25]
	v_pk_mul_f32 v[18:19], v[16:17], v[36:37]
	s_mov_b64 s[8:9], -1
	s_and_b64 vcc, exec, s[6:7]
	v_cvt_pk_bf16_f32 v16, v20, v21
	v_cvt_pk_bf16_f32 v17, v22, v23
	v_cvt_pk_bf16_f32 v18, v18, v19
	v_cvt_pk_bf16_f32 v19, v24, v25
	s_cbranch_vccnz .LBB0_911
	v_ashrrev_i32_e32 v53, 31, v52
	v_lshlrev_b64 v[20:21], 14, v[52:53]
	v_lshl_add_u64 v[20:21], s[16:17], 0, v[20:21]
	v_mov_b32_e32 v35, v137
	v_lshl_add_u64 v[20:21], v[20:21], 0, v[34:35]
	s_nop 0
	v_readfirstlane_b32 s98, v20
	v_readfirstlane_b32 s99, v21
	s_mov_b64 s[8:9], 0
	ds_write_b16 v234, v16
	ds_write_b16_d16_hi v234, v16 offset:32
	ds_write_b16 v234, v17 offset:64
	ds_write_b16_d16_hi v234, v17 offset:96
	ds_write_b16 v234, v18 offset:128
	ds_write_b16_d16_hi v234, v18 offset:160
	ds_write_b16 v234, v19 offset:192
	ds_write_b16_d16_hi v234, v19 offset:224
	ds_read_b128 v[240:243], v235
	s_waitcnt lgkmcnt(0)
	global_store_dwordx4 v236, v[240:243], s[98:99]

; __device__ __forceinline__ unsigned cvt_pk_bf16(float lo, float hi) { f32x2_t v = {lo, hi}; bf16x2_t b = __builtin_convertvector(v, bf16x2_t); return __builtin_bit_cast(unsigned, b); }
; __device__ __forceinline__ int p16(int k) { return ((k >> 2) & 1) * 8 + (k >> 3) * 4 + (k & 3); }
; __device__ __forceinline__ v4u pack8(f32x4 a, f32x4 b) { v4u r; r.x = cvt_pk_bf16(a[0], a[1]); r.y = cvt_pk_bf16(a[2], a[3]); r.z = cvt_pk_bf16(b[0], b[1]); r.w = cvt_pk_bf16(b[2], b[3]); return r; }
;     __device__ __forceinline__ void operator()(const f32x4 (&acc)[2][2][4][2], const Unit& u, int wr, int wc, int fr, int fq) const {
;     ...
;                 const int row = row0 + ai * 128 + m * 16; const int b = row >> 13, pos = row & (SEQ - 1), pp = (pos & ~15) | p16(pos & 15);
;                 const f32x4 pa = *(const f32x4*)(sskv + (size_t)row * 8), pb = *(const f32x4*)(sskv + (size_t)row * 8 + 4);
;                 const float rs = rsqrtf((((pa[0] + pa[1]) + (pa[2] + pa[3])) + ((pb[0] + pb[1]) + (pb[2] + pb[3]))) * (1.f / 256.f) + EPS);
; #pragma unroll
;                 for (int bj = 0; bj < 2; ++bj) {
;                     const int head = 2 * u.pn + bj;
;                     const f32x4 v0 = acc[ai][bj][m][0] * rs, v1 = acc[ai][bj][m][1] * rs;
;                     if (wc < 2) {
;                         *(v4u*)(Km + (size_t)row * 768 + head * 96 + 32 * wc + 8 * fq) = pack8(v0, v1);
;                     } else {
;                         bf16* base = VmT + ((size_t)((b * 8 + head) * 64 + 32 * (wc - 2) + 8 * fq)) * SEQ + pp;
;                         const unsigned w0_ = cvt_pk_bf16(v0[0], v0[1]), w1_ = cvt_pk_bf16(v0[2], v0[3]), w2_ = cvt_pk_bf16(v1[0], v1[1]), w3_ = cvt_pk_bf16(v1[2], v1[3]);
;                         base[0] = (bf16)(w0_ & 0xffffu); base[(size_t)SEQ] = (bf16)(w0_ >> 16); base[(size_t)2 * SEQ] = (bf16)(w1_ & 0xffffu); base[(size_t)3 * SEQ] = (bf16)(w1_ >> 16);
;                         base[(size_t)4 * SEQ] = (bf16)(w2_ & 0xffffu); base[(size_t)5 * SEQ] = (bf16)(w2_ >> 16); base[(size_t)6 * SEQ] = (bf16)(w3_ & 0xffffu); base[(size_t)7 * SEQ] = (bf16)(w3_ >> 16);
.LBB0_913:
	s_nop 1
	v_add_u32_e32 v18, 0xb0, v144
	v_ashrrev_i32_e32 v19, 31, v18
	v_lshlrev_b64 v[16:17], 5, v[18:19]
	v_lshl_add_u64 v[16:17], s[82:83], 0, v[16:17]
	global_load_dwordx4 v[20:23], v[16:17], off
	global_load_dwordx4 v[24:27], v[16:17], off offset:16
	v_and_or_b32 v28, v18, s3, v149
	s_mov_b64 s[8:9], -1
	s_waitcnt vmcnt(1)
	v_mov_b32_e32 v16, v20
	s_waitcnt vmcnt(0)
	v_mov_b32_e32 v17, v24
	v_mov_b32_e32 v24, v21
	v_mov_b32_e32 v20, v22
	v_mov_b32_e32 v21, v26
	v_mov_b32_e32 v26, v23
	v_pk_add_f32 v[16:17], v[16:17], v[24:25]
	v_pk_add_f32 v[20:21], v[20:21], v[26:27]
	s_nop 0
	v_pk_add_f32 v[16:17], v[16:17], v[20:21]
	s_nop 0
	v_add_f32_e32 v16, v16, v17
	v_fmamk_f32 v16, v16, 0x3b800000, v154
	v_cmp_gt_f32_e32 vcc, s72, v16
	v_mul_f32_e32 v17, 0x4b800000, v16
	s_nop 0
	v_cndmask_b32_e32 v16, v16, v17, vcc
	v_rsq_f32_e32 v16, v16
	s_nop 0
	v_mul_f32_e32 v17, 0x45800000, v16
	v_cndmask_b32_e32 v16, v16, v17, vcc
	v_pk_mul_f32 v[14:15], v[14:15], v[16:17] op_sel_hi:[1,0]
	v_pk_mul_f32 v[20:21], v[12:13], v[16:17] op_sel_hi:[1,0]
	v_pk_mul_f32 v[22:23], v[10:11], v[16:17] op_sel_hi:[1,0]
	v_pk_mul_f32 v[10:11], v[8:9], v[16:17] op_sel_hi:[1,0]
	s_and_b64 vcc, exec, s[6:7]
	v_lshlrev_b32_e32 v12, 1, v28
	v_cvt_pk_bf16_f32 v8, v20, v21
	v_cvt_pk_bf16_f32 v9, v14, v15
	v_cvt_pk_bf16_f32 v10, v10, v11
	v_cvt_pk_bf16_f32 v11, v22, v23
	s_cbranch_vccnz .LBB0_915
	v_ashrrev_i32_e32 v61, 31, v60
	v_lshlrev_b64 v[14:15], 14, v[60:61]
	v_lshl_add_u64 v[14:15], s[16:17], 0, v[14:15]
	v_mov_b32_e32 v13, v137
	v_lshl_add_u64 v[14:15], v[14:15], 0, v[12:13]
	s_nop 0
	v_readfirstlane_b32 s98, v14
	v_readfirstlane_b32 s99, v15
	s_mov_b64 s[8:9], 0
	ds_write_b16 v234, v8
	ds_write_b16_d16_hi v234, v8 offset:32
	ds_write_b16 v234, v9 offset:64
	ds_write_b16_d16_hi v234, v9 offset:96
	ds_write_b16 v234, v10 offset:128
	ds_write_b16_d16_hi v234, v10 offset:160
	ds_write_b16 v234, v11 offset:192
	ds_write_b16_d16_hi v234, v11 offset:224
	ds_read_b128 v[240:243], v235
	s_waitcnt lgkmcnt(0)
	global_store_dwordx4 v236, v[240:243], s[98:99]

; __device__ __forceinline__ unsigned cvt_pk_bf16(float lo, float hi) { f32x2_t v = {lo, hi}; bf16x2_t b = __builtin_convertvector(v, bf16x2_t); return __builtin_bit_cast(unsigned, b); }
; __device__ __forceinline__ v4u pack8(f32x4 a, f32x4 b) { v4u r; r.x = cvt_pk_bf16(a[0], a[1]); r.y = cvt_pk_bf16(a[2], a[3]); r.z = cvt_pk_bf16(b[0], b[1]); r.w = cvt_pk_bf16(b[2], b[3]); return r; }
;     __device__ __forceinline__ void operator()(const f32x4 (&acc)[2][2][4][2], const Unit& u, int wr, int wc, int fr, int fq) const {
;     ...
;                 for (int bj = 0; bj < 2; ++bj) {
;                     const int head = 2 * u.pn + bj;
;                     const f32x4 v0 = acc[ai][bj][m][0] * rs, v1 = acc[ai][bj][m][1] * rs;
;                     if (wc < 2) {
;                         *(v4u*)(Km + (size_t)row * 768 + head * 96 + 32 * wc + 8 * fq) = pack8(v0, v1);
;                     } else {
;                         bf16* base = VmT + ((size_t)((b * 8 + head) * 64 + 32 * (wc - 2) + 8 * fq)) * SEQ + pp;
;                         const unsigned w0_ = cvt_pk_bf16(v0[0], v0[1]), w1_ = cvt_pk_bf16(v0[2], v0[3]), w2_ = cvt_pk_bf16(v1[0], v1[1]), w3_ = cvt_pk_bf16(v1[2], v1[3]);
;                         base[0] = (bf16)(w0_ & 0xffffu); base[(size_t)SEQ] = (bf16)(w0_ >> 16); base[(size_t)2 * SEQ] = (bf16)(w1_ & 0xffffu); base[(size_t)3 * SEQ] = (bf16)(w1_ >> 16);
;                         base[(size_t)4 * SEQ] = (bf16)(w2_ & 0xffffu); base[(size_t)5 * SEQ] = (bf16)(w2_ >> 16); base[(size_t)6 * SEQ] = (bf16)(w3_ & 0xffffu); base[(size_t)7 * SEQ] = (bf16)(w3_ >> 16);
.LBB0_917:
	v_mov_b32_e32 v17, v16
	s_nop 0
	v_mov_b32_e32 v8, v16
	v_mov_b32_e32 v9, v16
	v_pk_mul_f32 v[6:7], v[6:7], v[8:9]
	v_pk_mul_f32 v[4:5], v[4:5], v[16:17]
	v_pk_mul_f32 v[8:9], v[2:3], v[8:9]
	v_pk_mul_f32 v[2:3], v[0:1], v[16:17]
	s_mov_b64 s[8:9], -1
	s_and_b64 vcc, exec, s[6:7]
	v_cvt_pk_bf16_f32 v0, v4, v5
	v_cvt_pk_bf16_f32 v1, v6, v7
	v_cvt_pk_bf16_f32 v2, v2, v3
	v_cvt_pk_bf16_f32 v3, v8, v9
	s_cbranch_vccnz .LBB0_919
	v_ashrrev_i32_e32 v53, 31, v52
	v_lshlrev_b64 v[4:5], 14, v[52:53]
	v_lshl_add_u64 v[4:5], s[16:17], 0, v[4:5]
	v_mov_b32_e32 v13, v137
	v_lshl_add_u64 v[4:5], v[4:5], 0, v[12:13]
	s_nop 0
	v_readfirstlane_b32 s98, v4
	v_readfirstlane_b32 s99, v5
	s_mov_b64 s[8:9], 0
	ds_write_b16 v234, v0
	ds_write_b16_d16_hi v234, v0 offset:32
	ds_write_b16 v234, v1 offset:64
	ds_write_b16_d16_hi v234, v1 offset:96
	ds_write_b16 v234, v2 offset:128
	ds_write_b16_d16_hi v234, v2 offset:160
	ds_write_b16 v234, v3 offset:192
	ds_write_b16_d16_hi v234, v3 offset:224
	ds_read_b128 v[240:243], v235
	s_waitcnt lgkmcnt(0)
	global_store_dwordx4 v236, v[240:243], s[98:99]

; __global__ void __launch_bounds__(512, 2) fwd_megakernel(Args a) {
;     extern __shared__ __attribute__((aligned(16))) unsigned char lds_raw[];
	.amdhsa_kernel _Z14fwd_megakernel4Args
		.amdhsa_group_segment_fixed_size 0
		.amdhsa_private_segment_fixed_size 0
		.amdhsa_kernarg_size 448
		.amdhsa_user_sgpr_count 2
		.amdhsa_user_sgpr_dispatch_ptr 0
		.amdhsa_user_sgpr_queue_ptr 0
		.amdhsa_user_sgpr_kernarg_segment_ptr 1
		.amdhsa_user_sgpr_dispatch_id 0
		.amdhsa_user_sgpr_kernarg_preload_length 0
		.amdhsa_user_sgpr_kernarg_preload_offset 0
		.amdhsa_user_sgpr_private_segment_size 0
		.amdhsa_uses_dynamic_stack 0
		.amdhsa_enable_private_segment 0
		.amdhsa_system_sgpr_workgroup_id_x 1
		.amdhsa_system_sgpr_workgroup_id_y 0
		.amdhsa_system_sgpr_workgroup_id_z 0
		.amdhsa_system_sgpr_workgroup_info 0
		.amdhsa_system_vgpr_workitem_id 2
		.amdhsa_next_free_vgpr 252
		.amdhsa_next_free_sgpr 100
		.amdhsa_accum_offset 252
		.amdhsa_reserve_vcc 1
		.amdhsa_float_round_mode_32 0
		.amdhsa_float_round_mode_16_64 0
		.amdhsa_float_denorm_mode_32 3
		.amdhsa_float_denorm_mode_16_64 3
		.amdhsa_dx10_clamp 1
		.amdhsa_ieee_mode 1
		.amdhsa_fp16_overflow 0
		.amdhsa_tg_split 0
		.amdhsa_exception_fp_ieee_invalid_op 0
		.amdhsa_exception_fp_denorm_src 0
		.amdhsa_exception_fp_ieee_div_zero 0
		.amdhsa_exception_fp_ieee_overflow 0
		.amdhsa_exception_fp_ieee_underflow 0
		.amdhsa_exception_fp_ieee_inexact 0
		.amdhsa_exception_int_div_zero 0
	.end_amdhsa_kernel

; __global__ void __launch_bounds__(512, 2) fwd_megakernel(Args a) {
;     extern __shared__ __attribute__((aligned(16))) unsigned char lds_raw[];
amdhsa.kernels:
  - .agpr_count:     0
    .args:
      - .offset:         0
        .size:           192
        .value_kind:     by_value
      - .offset:         192
        .size:           4
        .value_kind:     hidden_block_count_x
      - .offset:         196
        .size:           4
        .value_kind:     hidden_block_count_y
      - .offset:         200
        .size:           4
        .value_kind:     hidden_block_count_z
      - .offset:         204
        .size:           2
        .value_kind:     hidden_group_size_x
      - .offset:         206
        .size:           2
        .value_kind:     hidden_group_size_y
      - .offset:         208
        .size:           2
        .value_kind:     hidden_group_size_z
      - .offset:         210
        .size:           2
        .value_kind:     hidden_remainder_x
      - .offset:         212
        .size:           2
        .value_kind:     hidden_remainder_y
      - .offset:         214
        .size:           2
        .value_kind:     hidden_remainder_z
      - .offset:         232
        .size:           8
        .value_kind:     hidden_global_offset_x
      - .offset:         240
        .size:           8
        .value_kind:     hidden_global_offset_y
      - .offset:         248
        .size:           8
        .value_kind:     hidden_global_offset_z
      - .offset:         256
        .size:           2
        .value_kind:     hidden_grid_dims
      - .offset:         280
        .size:           8
        .value_kind:     hidden_multigrid_sync_arg
      - .offset:         312
        .size:           4
        .value_kind:     hidden_dynamic_lds_size
    .group_segment_fixed_size: 0
    .kernarg_segment_align: 8
    .kernarg_segment_size: 448
    .language:       OpenCL C
    .language_version:
      - 2
      - 0
    .max_flat_workgroup_size: 512
    .name:           _Z14fwd_megakernel4Args
    .private_segment_fixed_size: 0
    .sgpr_count:     106
    .sgpr_spill_count: 66
    .symbol:         _Z14fwd_megakernel4Args.kd
    .uniform_work_group_size: 1
    .uses_dynamic_stack: false
    .vgpr_count:     252
    .vgpr_spill_count: 0
    .wavefront_size: 64
